# SO10: virtual state tiles stage their chunk outputs through LDS and write one global_store_dwordx4 per chunk instead of eight global_store_short (on SO7)
# baseline (speedup 1.0000x reference)
.LBB0_438:
	s_andn2_b64 vcc, exec, s[90:91]
	s_cbranch_vccnz .LBB0_446
	v_and_b32_e32 v38, 0x3e0, v135
	s_movk_i32 s10, 0xc00
	v_and_b32_e32 v37, 0x3e0, v133
	v_add3_u32 v86, v38, v127, s10
	s_movk_i32 s10, 0x800
	v_lshl_add_u32 v82, v128, 5, v127
	v_and_b32_e32 v36, 0x3e0, v131
	v_lshl_add_u32 v34, v125, 8, s35
	v_add3_u32 v87, v37, v127, s10
	s_movk_i32 s10, 0x400
	v_add_lshl_u32 v83, v34, v128, 1
	v_add_u32_e32 v84, 0x1c800, v82
	v_add_u32_e32 v85, s70, v82
	v_add3_u32 v88, v36, v127, s10
	s_mov_b32 s14, 0
	v_lshlrev_b32_e32 v106, 1, v128
	v_mov_b32_e32 v89, v127
	v_mov_b32_e32 v90, v82
	s_lshl_b32 s10, s1, 10
	s_add_i32 s10, s10, 0x7800
	v_lshl_add_u32 v66, v125, 8, v106
	v_lshlrev_b32_e32 v68, 4, v1
	v_lshrrev_b32_e32 v70, 2, v1
	v_and_b32_e32 v72, 3, v1
	v_add_u32_e32 v66, s10, v66
	v_lshlrev_b32_e32 v70, 12, v70
	v_add_u32_e32 v68, s10, v68
	v_lshl_add_u32 v70, v72, 4, v70
	s_branch .LBB0_441

.LBB0_443:
	s_andn2_b64 vcc, exec, s[10:11]
	s_cbranch_vccnz .LBB0_440
	s_add_i32 s10, s67, s14
	s_ashr_i32 s11, s10, 31
	s_lshl_b64 s[10:11], s[10:11], 12
	s_add_u32 s10, s38, s10
	s_addc_u32 s11, s39, s11
	s_lshl_b32 s15, s59, 1
	s_add_u32 s10, s10, s15
	s_addc_u32 s11, s11, 0
	s_add_u32 s10, s10, s72
	s_addc_u32 s11, s11, 0
	s_add_u32 s10, s10, 0x4500800
	s_addc_u32 s11, s11, 0
	v_cvt_pk_f16_f32 v34, v42, v43
	v_cvt_pk_f16_f32 v35, v44, v45
	v_cvt_pk_f16_f32 v36, v46, v47
	v_cvt_pk_f16_f32 v37, v48, v49
	ds_write_b16 v66, v34
	ds_write_b16_d16_hi v66, v34 offset:64
	ds_write_b16 v66, v35 offset:128
	ds_write_b16_d16_hi v66, v35 offset:192
	ds_write_b16 v66, v36 offset:512
	ds_write_b16_d16_hi v66, v36 offset:576
	ds_write_b16 v66, v37 offset:640
	ds_write_b16_d16_hi v66, v37 offset:704
	ds_read_b128 v[38:41], v68
	s_waitcnt lgkmcnt(0)
	global_store_dwordx4 v70, v[38:41], s[10:11]
	s_branch .LBB0_440
